# v10: + SWA-layer V^T tiles moved to the CUs with fewer QK tiles
# baseline (speedup 1.0000x reference)
; #define ws (KP()->ws)
;     __host__ __device__ bool next(int i, Unit& u) const {
;         const long L = (long)i * G + c; if (L >= nwg) return false;
;         int wgid = (int)L; { const int q = nwg / NXCD, r = nwg % NXCD, xcd = wgid % NXCD, off = wgid / NXCD; wgid = (xcd < r ? xcd * (q + 1) : r * (q + 1) + (xcd - r) * q) + off; }
; __global__ void __launch_bounds__(NTHREADS, 2) trunk_fwd(Params p) {
;     ...
;         {
;             const int vrows = (kind == 2) ? 256 : 1024;
;             pg8::Gemm g{wl + W_IN / 2 + (size_t)(nqkv - vrows) * DM, HB, vrows, MTOK, DM}; pg8::StaticOrder S; S.init(vrows, MTOK, G, (int)blockIdx.x);
;             pg8::EpiVT E{ws + WS_VT, nkv, (kind == 2) ? 128 : 0, rsq1, bias1 + (nqkv - vrows), 3072};
;             pg8::gemm_phase<pg8::EpiVT, pg8::StaticOrder, true, true>(lds, g, S, E, wave_s);
.LBB0_306:
	s_xor_b32 s98, s2, 0x80
	s_mov_b64 s[4:5], s[0:1]
	s_load_dwordx2 s[10:11], s[4:5], 0x90
	s_mov_b64 s[4:5], s[0:1]
	s_load_dwordx2 s[4:5], s[4:5], 0x90
	s_lshl_b32 s6, s41, 7
	v_mbcnt_lo_u32_b32 v0, -1, 0
	v_mbcnt_hi_u32_b32 v0, -1, v0
	s_cmp_lt_i32 s98, s6
	v_add_u32_e32 v2, s94, v0
	s_cselect_b64 s[12:13], -1, 0
	s_cmp_ge_i32 s98, s6
	v_readfirstlane_b32 s7, v2
	s_cbranch_scc1 .LBB0_312
	v_readlane_b32 s18, v242, 5
	v_readlane_b32 s19, v242, 6
	s_mov_b64 s[14:15], -1
	s_and_b64 vcc, exec, s[18:19]
	s_cbranch_vccz .LBB0_309
	s_and_b64 s[14:15], s[16:17], exec
	s_cselect_b32 s14, 4, 6
	v_readlane_b32 s15, v242, 30
	s_lshl_b32 s18, s15, s14
	s_mov_b64 s[14:15], 0

;     __host__ __device__ bool next(int i, Unit& u) const {
;         const long L = (long)i * G + c; if (L >= nwg) return false;
;         int wgid = (int)L; { const int q = nwg / NXCD, r = nwg % NXCD, xcd = wgid % NXCD, off = wgid / NXCD; wgid = (xcd < r ? xcd * (q + 1) : r * (q + 1) + (xcd - r) * q) + off; }
;         const int nig = WGM * nN, gid = wgid / nig, fm = gid * WGM, gsz = (nM - fm) < WGM ? (nM - fm) : WGM;
;         u.pm = fm + ((wgid % nig) % gsz); u.pn = (wgid % nig) / gsz; return true;
.LBB0_311:
	v_readlane_b32 s14, v242, 22
	s_xor_b32 s14, s14, 16
	s_add_i32 s14, s18, s14
	s_ashr_i32 s15, s14, 31
	s_lshr_b32 s15, s15, 22
	s_add_i32 s15, s14, s15
	s_ashr_i32 s18, s15, 10
	s_lshl_b32 s18, s18, 3
	s_sub_i32 s19, s41, s18
	s_min_u32 s19, s19, 8
	s_and_b32 s15, s15, 0xfffffc00
	s_sub_i32 s20, s14, s15
	v_cvt_f32_ubyte0_e32 v4, s19
	v_cvt_f32_i32_e32 v3, s20
	v_rcp_iflag_f32_e32 v5, v4
	s_ashr_i32 s14, s20, 30
	s_or_b32 s21, s14, 1
	v_mul_f32_e32 v5, v3, v5
	v_trunc_f32_e32 v5, v5
	v_fma_f32 v3, -v5, v4, v3
	v_cvt_i32_f32_e32 v5, v5
	v_cmp_ge_f32_e64 s[14:15], |v3|, v4
	s_and_b64 s[14:15], s[14:15], exec
	s_cselect_b32 s14, s21, 0
	v_readfirstlane_b32 s15, v5
	s_add_i32 s14, s15, s14
	s_sext_i32_i16 s24, s14
	s_mul_i32 s14, s14, s19
	s_sub_i32 s14, s20, s14
	s_sext_i32_i16 s14, s14
	s_add_i32 s26, s18, s14

;     __host__ __device__ bool next(int i, Unit& u) const {
;         const long L = (long)i * G + c; if (L >= nwg) return false;
;         int wgid = (int)L; { const int q = nwg / NXCD, r = nwg % NXCD, xcd = wgid % NXCD, off = wgid / NXCD; wgid = (xcd < r ? xcd * (q + 1) : r * (q + 1) + (xcd - r) * q) + off; }
;         const int nig = WGM * nN, gid = wgid / nig, fm = gid * WGM, gsz = (nM - fm) < WGM ? (nM - fm) : WGM;
;         u.pm = fm + ((wgid % nig) % gsz); u.pn = (wgid % nig) / gsz; return true;
.LBB0_318:
	s_add_i32 s50, s50, 1
	s_mul_i32 s4, s50, s63
	s_mul_hi_u32 s5, s50, s42
	s_add_i32 s5, s5, s4
	s_mul_i32 s4, s50, s42
	s_add_u32 s20, s4, s98
	s_addc_u32 s21, s5, s60
	v_mov_b64_e32 v[2:3], s[6:7]
	v_cmp_ge_i64_e32 vcc, s[20:21], v[2:3]
	v_cmp_lt_i64_e64 s[4:5], s[20:21], v[2:3]
	s_cbranch_vccnz .LBB0_324
	s_ashr_i32 s16, s20, 31
	s_lshr_b32 s16, s16, 29
	s_add_i32 s18, s20, s16
	s_and_b32 s16, s18, -8
	s_sub_i32 s19, s20, s16
	s_cmp_gt_i32 s19, -1
	s_mov_b64 s[16:17], -1
	s_cbranch_scc0 .LBB0_321
	s_lshl_b32 s20, s19, s96
	s_mov_b64 s[16:17], 0
